# m3: conv weights and bias staged once per phase in LDS and read per chunk with ds_read_b128 instead of 20 global loads per thread
# speedup vs baseline: 1.0072x; 1.0015x over previous
.LBB0_446:
	s_or_b64 exec, exec, s[0:1]
	s_mov_b64 s[2:3], s[72:73]
	v_readlane_b32 s12, v254, 35
	v_readlane_b32 s0, v254, 60
	s_and_b64 vcc, exec, s[58:59]
	s_waitcnt lgkmcnt(0)
	s_barrier
	v_readlane_b32 s1, v254, 61
	s_cbranch_vccz .LBB0_494
	s_load_dwordx2 s[0:1], s[2:3], 0x88
	s_load_dwordx8 s[4:11], s[2:3], 0x48
	s_nop 0
	s_load_dwordx2 s[2:3], s[2:3], 0x68
	s_mov_b32 s39, s70
	s_waitcnt lgkmcnt(0)
	s_add_u32 s14, s0, 0xc000000
	s_addc_u32 s15, s1, 0
	s_add_u32 s33, s0, 0xe000000
	s_addc_u32 s36, s1, 0
	s_lshl_b32 s16, s12, 12
	s_ashr_i32 s17, s16, 31
	s_lshl_b64 s[16:17], s[16:17], 2
	s_add_u32 s16, s4, s16
	s_addc_u32 s17, s5, s17
	s_lshl_b32 s4, s12, 10
	s_ashr_i32 s5, s4, 31
	s_lshl_b64 s[4:5], s[4:5], 2
	s_add_u32 s18, s6, s4
	s_addc_u32 s19, s7, s5
	s_add_u32 s37, s0, 0x18200000
	s_addc_u32 s38, s1, 0
	s_lshl_b32 s4, s12, 7
	s_ashr_i32 s5, s4, 31
	s_lshl_b64 s[4:5], s[4:5], 2
	s_add_u32 s20, s2, s4
	s_addc_u32 s21, s3, s5
	s_add_u32 s22, s0, 0x12000000
	s_addc_u32 s23, s1, 0
	s_add_u32 s24, s0, 0x4000000
	s_addc_u32 s25, s1, 0
	s_lshl_b32 s2, s12, 3
	s_ashr_i32 s3, s2, 31
	s_lshl_b64 s[2:3], s[2:3], 2
	s_add_u32 s26, s10, s2
	s_addc_u32 s27, s11, s3
	s_add_u32 s28, s8, s2
	s_addc_u32 s29, s9, s3
	s_add_u32 s30, s0, 0x18000000
	s_addc_u32 s31, s1, 0
	v_lshlrev_b32_e32 v0, 4, v194
	global_load_dwordx4 v[4:7], v0, s[16:17]
	s_add_u32 s90, s16, 0x2000
	s_addc_u32 s91, s17, 0
	global_load_dwordx4 v[8:11], v0, s[90:91]
	v_cmp_gt_u32_e32 vcc, 0x100, v194
	s_and_saveexec_b64 s[92:93], vcc
	global_load_dwordx4 v[12:15], v0, s[18:19]
	s_mov_b64 exec, s[92:93]
	v_add_u32_e32 v1, 0x1a000, v0
	s_waitcnt vmcnt(0)
	ds_write_b128 v1, v[4:7]
	ds_write_b128 v1, v[8:11] offset:8192
	s_and_saveexec_b64 s[92:93], vcc
	ds_write_b128 v1, v[12:15] offset:16384
	s_mov_b64 exec, s[92:93]
	s_waitcnt lgkmcnt(0)
	s_barrier
	s_branch .LBB0_449

.LBB0_449:
	s_ashr_i32 s2, s39, 10
	s_and_b32 s41, s39, 0x7f
	s_ashr_i32 s3, s2, 31
	v_mov_b32_e32 v23, v194
	s_lshl_b64 s[34:35], s[2:3], 13
	s_lshl_b32 s2, s41, 6
	s_bfe_u32 s42, s39, 0x30007
	v_readfirstlane_b32 s40, v23
	s_or_b32 s34, s34, s2
	v_lshrrev_b32_e32 v209, 3, v23
	v_and_b32_e32 v210, 7, v23
	v_lshlrev_b32_e32 v211, 4, v210
	v_lshl_or_b32 v190, v209, 15, v211
	v_lshlrev_b32_e32 v191, 4, v23
	v_lshl_or_b32 v192, v209, 11, v211
	v_add_u32_e32 v193, 0x1000, v192
	v_lshlrev_b32_e32 v208, 5, v210
	s_lshl_b32 s90, s42, 7
	s_or_b32 s90, s90, 0x400
	s_lshl_b64 s[52:53], s[34:35], 1
	s_add_u32 s52, s33, s52
	s_addc_u32 s53, s36, s53
	s_lshl_b32 s91, s90, 15
	s_add_u32 s52, s52, s91
	s_addc_u32 s53, s53, 0
	s_add_u32 s54, s52, 0x200000
	s_addc_u32 s55, s53, 0
	global_load_dwordx4 v[44:47], v190, s[52:53]
	global_load_dwordx4 v[48:51], v190, s[54:55]
	s_mul_i32 s92, s39, 0x4080
	s_mul_hi_i32 s93, s39, 0x4080
	s_add_u32 s92, s37, s92
	s_addc_u32 s93, s38, s93
	global_load_dwordx4 v[52:55], v191, s[92:93]
	s_add_u32 s94, s92, 0x2000
	s_addc_u32 s95, s93, 0
	global_load_dwordx4 v[56:59], v191, s[94:95]
	s_add_u32 s94, s92, 0x4000
	s_addc_u32 s95, s93, 0
	v_cmp_gt_u32_e32 vcc, 8, v23
	s_and_saveexec_b64 s[96:97], vcc
	global_load_dwordx4 v[60:63], v191, s[94:95]
	s_mov_b64 exec, s[96:97]
	s_sub_u32 s92, s34, 3
	s_subb_u32 s93, s35, 0
	s_lshl_b64 s[92:93], s[92:93], 11
	s_add_u32 s92, s14, s92
	s_addc_u32 s93, s15, s93
	s_lshl_b32 s91, s42, 7
	s_add_u32 s92, s92, s91
	s_addc_u32 s93, s93, 0
	s_cmp_lg_u32 s41, 0
	s_cselect_b64 s[54:55], -1, 0
	v_cmp_lt_u32_e32 vcc, 2, v209
	s_or_b64 s[46:47], s[54:55], vcc
	v_cmp_lt_u32_e32 vcc, 1, v209
	s_or_b64 s[48:49], s[54:55], vcc
	v_cmp_lt_u32_e32 vcc, 0, v209
	s_or_b64 s[50:51], s[54:55], vcc
	s_mov_b64 s[96:97], exec
	s_and_b64 exec, s[96:97], s[46:47]
	global_load_dwordx4 v[80:83], v192, s[92:93]
	global_load_dwordx4 v[128:131], v192, s[92:93] offset:1024
	s_and_b64 exec, s[96:97], s[48:49]
	global_load_dwordx4 v[92:95], v192, s[92:93] offset:2048
	global_load_dwordx4 v[140:143], v192, s[92:93] offset:3072
	s_and_b64 exec, s[96:97], s[50:51]
	global_load_dwordx4 v[104:107], v193, s[92:93]
	global_load_dwordx4 v[152:155], v193, s[92:93] offset:1024
	s_mov_b64 exec, s[96:97]
	global_load_dwordx4 v[116:119], v193, s[92:93] offset:2048
	global_load_dwordx4 v[178:181], v193, s[92:93] offset:3072
	s_lshr_b32 s90, s40, 6
	s_lshl_b32 s90, s90, 3
	s_add_u32 s90, s34, s90
	s_addc_u32 s91, s35, 0
	s_lshl_b64 s[90:91], s[90:91], 11
	s_add_u32 s90, s22, s90
	s_addc_u32 s91, s23, s91
	s_lshl_b32 s92, s42, 8
	v_and_b32_e32 v232, 63, v23
	v_lshlrev_b32_e32 v233, 3, v232
	v_lshl_or_b32 v232, v232, 2, s92
	global_load_dword v224, v232, s[90:91]
	global_load_dword v225, v232, s[90:91] offset:2048
	s_add_u32 s90, s90, 0x1000
	s_addc_u32 s91, s91, 0
	global_load_dword v226, v232, s[90:91]
	global_load_dword v227, v232, s[90:91] offset:2048
	s_add_u32 s90, s90, 0x1000
	s_addc_u32 s91, s91, 0
	global_load_dword v228, v232, s[90:91]
	global_load_dword v229, v232, s[90:91] offset:2048
	s_add_u32 s90, s90, 0x1000
	s_addc_u32 s91, s91, 0
	global_load_dword v230, v232, s[90:91]
	global_load_dword v231, v232, s[90:91] offset:2048
	global_load_dwordx2 v[234:235], v233, s[20:21]
	s_cmp_gt_u32 s40, 63
	v_and_b32_e32 v22, 63, v23
	s_cbranch_scc1 .LBB0_451
	v_or_b32_e32 v0, s34, v22
	v_mov_b32_e32 v1, s35
	v_lshlrev_b64 v[0:1], 6, v[0:1]
	v_lshl_add_u64 v[0:1], s[30:31], 0, v[0:1]
	s_lshl_b32 s86, s42, 2
	v_lshl_add_u64 v[0:1], v[0:1], 0, s[86:87]
	v_mov_b32_e32 v3, s86
	global_load_dword v2, v[0:1], off offset:32
	global_load_dword v4, v3, s[26:27]
	s_nop 0
	global_load_dword v0, v[0:1], off
	s_nop 0
	global_load_dword v1, v3, s[28:29]
	s_lshl_b32 s98, s39, 4
	s_add_u32 s98, s0, s98
	s_addc_u32 s99, s1, 0
	v_mov_b32_e32 v41, 0x18100000
	global_load_dword v42, v41, s[98:99] offset:8
	s_mov_b32 s2, 0x3f317218
	s_waitcnt vmcnt(2)
	v_add_f32_e32 v2, v2, v4
	s_waitcnt vmcnt(0)
	v_add_f32_e32 v1, v0, v1
	v_min_f32_e32 v0, 0, v2
	v_mul_f32_e64 v2, |v2|, s79
	v_exp_f32_e32 v4, v2
	s_nop 0
	v_add_f32_e32 v5, 1.0, v4
	v_add_f32_e32 v2, -1.0, v5
	v_sub_f32_e32 v3, v2, v5
	v_add_f32_e32 v3, 1.0, v3
	v_sub_f32_e32 v2, v4, v2
	v_add_f32_e32 v6, v2, v3
	v_frexp_mant_f32_e32 v2, v5
	v_cmp_gt_f32_e32 vcc, s85, v2
	v_cvt_f64_f32_e32 v[2:3], v5
	v_frexp_exp_i32_f64_e32 v2, v[2:3]
	v_subbrev_co_u32_e32 v2, vcc, 0, v2, vcc
	v_sub_u32_e32 v3, 0, v2
	v_ldexp_f32 v5, v5, v3
	v_ldexp_f32 v3, v6, v3
	v_add_f32_e32 v6, -1.0, v5
	v_add_f32_e32 v7, 1.0, v6
	v_sub_f32_e32 v7, v5, v7
	v_add_f32_e32 v7, v3, v7
	v_add_f32_e32 v8, v6, v7
	v_sub_f32_e32 v6, v8, v6
	v_sub_f32_e32 v6, v7, v6
	v_add_f32_e32 v7, 1.0, v5
	v_add_f32_e32 v9, -1.0, v7
	v_sub_f32_e32 v5, v5, v9
	v_add_f32_e32 v3, v3, v5
	v_add_f32_e32 v5, v7, v3
	v_sub_f32_e32 v7, v5, v7
	v_sub_f32_e32 v3, v3, v7
	v_rcp_f32_e32 v7, v5
	v_cvt_f32_i32_e32 v2, v2
	v_mul_f32_e32 v9, v8, v7
	v_mul_f32_e32 v10, v5, v9
	v_fma_f32 v11, v9, v5, -v10
	v_fmac_f32_e32 v11, v9, v3
	v_add_f32_e32 v12, v10, v11
	v_sub_f32_e32 v13, v8, v12
	v_sub_f32_e32 v8, v8, v13
	v_sub_f32_e32 v10, v12, v10
	v_sub_f32_e32 v8, v8, v12
	v_add_f32_e32 v6, v6, v8
	v_sub_f32_e32 v8, v10, v11
	v_add_f32_e32 v6, v8, v6
	v_add_f32_e32 v8, v13, v6
	v_mul_f32_e32 v10, v7, v8
	v_mul_f32_e32 v11, v5, v10
	v_fma_f32 v5, v10, v5, -v11
	v_fmac_f32_e32 v5, v10, v3
	v_sub_f32_e32 v3, v13, v8
	v_add_f32_e32 v3, v6, v3
	v_add_f32_e32 v6, v11, v5
	v_sub_f32_e32 v12, v8, v6
	v_sub_f32_e32 v8, v8, v12
	v_sub_f32_e32 v11, v6, v11
	v_sub_f32_e32 v6, v8, v6
	v_add_f32_e32 v3, v3, v6
	v_sub_f32_e32 v5, v11, v5
	v_add_f32_e32 v3, v5, v3
	v_add_f32_e32 v5, v9, v10
	v_add_f32_e32 v3, v12, v3
	v_sub_f32_e32 v6, v5, v9
	v_mul_f32_e32 v3, v7, v3
	v_sub_f32_e32 v6, v10, v6
	v_add_f32_e32 v3, v6, v3
	v_mul_f32_e32 v9, 0x3f317218, v2
	v_add_f32_e32 v6, v5, v3
	v_fma_f32 v10, v2, s2, -v9
	v_mul_f32_e32 v7, v6, v6
	v_fmac_f32_e32 v10, 0xb102e308, v2
	v_sub_f32_e32 v2, v6, v5
	v_fmamk_f32 v8, v7, 0x3e9b6dac, v200
	v_sub_f32_e32 v2, v3, v2
	v_add_f32_e32 v3, v9, v10
	v_fmaak_f32 v8, v7, v8, 0x3f2aaada
	v_sub_f32_e32 v5, v3, v9
	v_ldexp_f32 v9, v6, 1
	v_mul_f32_e32 v6, v6, v7
	v_mul_f32_e32 v6, v6, v8
	v_add_f32_e32 v7, v9, v6
	v_sub_f32_e32 v8, v7, v9
	v_ldexp_f32 v2, v2, 1
	v_sub_f32_e32 v6, v6, v8
	v_add_f32_e32 v2, v2, v6
	v_add_f32_e32 v6, v7, v2
	v_sub_f32_e32 v7, v6, v7
	v_sub_f32_e32 v2, v2, v7
	v_add_f32_e32 v7, v3, v6
	v_sub_f32_e32 v8, v7, v3
	v_sub_f32_e32 v9, v7, v8
	v_sub_f32_e32 v5, v10, v5
	v_sub_f32_e32 v3, v3, v9
	v_sub_f32_e32 v6, v6, v8
	v_add_f32_e32 v3, v6, v3
	v_add_f32_e32 v6, v5, v2
	v_sub_f32_e32 v8, v6, v5
	v_sub_f32_e32 v9, v6, v8
	v_sub_f32_e32 v5, v5, v9
	v_sub_f32_e32 v2, v2, v8
	v_add_f32_e32 v3, v6, v3
	v_add_f32_e32 v2, v2, v5
	v_add_f32_e32 v5, v7, v3
	v_sub_f32_e32 v6, v5, v7
	v_sub_f32_e32 v3, v3, v6
	v_add_f32_e32 v2, v2, v3
	s_mov_b32 s2, 0x7f800000
	v_add_f32_e32 v2, v5, v2
	v_cmp_neq_f32_e32 vcc, s2, v4
	s_mov_b32 s2, 0x33800000
	v_add_u32_e32 v3, -1, v201
	v_cndmask_b32_e32 v2, v202, v2, vcc
	v_cmp_ngt_f32_e32 vcc, -1.0, v4
	s_nop 1
	v_cndmask_b32_e32 v2, v203, v2, vcc
	v_cmp_neq_f32_e32 vcc, -1.0, v4
	s_nop 1
	v_cndmask_b32_e32 v2, v204, v2, vcc
	v_cmp_lt_f32_e64 vcc, |v4|, s2
	s_lshl_b32 s2, s39, 2
	s_ashr_i32 s3, s2, 31
	v_cndmask_b32_e32 v2, v2, v4, vcc
	v_sub_f32_e32 v0, v0, v2
	v_mov_b32_e32 v4, v0
	s_nop 1
	v_add_f32_dpp v4, v0, v4 row_shr:1 row_mask:0xf bank_mask:0xf
	v_add_f32_dpp v4, v0, v4 row_shr:2 row_mask:0xf bank_mask:0xf
	v_add_f32_dpp v4, v0, v4 row_shr:3 row_mask:0xf bank_mask:0xf
	s_nop 1
	v_add_f32_dpp v4, v4, v4 row_shr:4 row_mask:0xf bank_mask:0xe
	s_nop 1
	v_add_f32_dpp v4, v4, v4 row_shr:8 row_mask:0xf bank_mask:0xc
	s_nop 1
	v_add_f32_dpp v4, v4, v4 row_bcast:15 row_mask:0xa bank_mask:0xf
	s_nop 1
	v_add_f32_dpp v4, v4, v4 row_bcast:31 row_mask:0xc bank_mask:0xf
	v_mov_b32_e32 v0, v4
	v_sub_f32_e32 v1, v1, v0
	v_mov_b32_e32 v3, v1
	s_nop 1
	v_max_f32_dpp v3, v1, v3 row_shr:1 row_mask:0xf bank_mask:0xf
	v_max_f32_dpp v3, v1, v3 row_shr:2 row_mask:0xf bank_mask:0xf
	v_max_f32_dpp v3, v1, v3 row_shr:3 row_mask:0xf bank_mask:0xf
	s_nop 1
	v_max_f32_dpp v3, v3, v3 row_shr:4 row_mask:0xf bank_mask:0xe
	s_nop 1
	v_max_f32_dpp v3, v3, v3 row_shr:8 row_mask:0xf bank_mask:0xc
	s_nop 1
	v_max_f32_dpp v3, v3, v3 row_bcast:15 row_mask:0xa bank_mask:0xf
	s_nop 1
	v_max_f32_dpp v3, v3, v3 row_bcast:31 row_mask:0xc bank_mask:0xf
	v_mov_b32_e32 v2, v3
	v_max_f32_e32 v2, v2, v2
	s_waitcnt vmcnt(0)
	v_mov_b32_e32 v3, v42
	v_max_f32_e32 v4, v3, v3
	v_max_f32_e32 v2, v4, v2
	v_lshl_add_u32 v4, v22, 2, 0
	v_add_u32_e32 v4, 0x19200, v4
	ds_write2st64_b32 v4, v1, v2 offset1:1
	v_sub_f32_e32 v1, v3, v2
	v_add_f32_e32 v0, v0, v2
	v_mul_f32_e32 v1, 0x3fb8aa3b, v1
	v_mul_f32_e32 v0, 0xbfb8aa3b, v0
	v_exp_f32_e32 v1, v1
	v_exp_f32_e32 v0, v0
	ds_write2st64_b32 v4, v1, v0 offset0:2 offset1:3
.LBB0_451:
	s_lshl_b32 s12, s42, 7
	s_lshl_b32 s91, s42, 8
	s_add_u32 s91, s91, 0x1a000
	v_add_u32_e32 v191, s91, v208
	ds_read_b128 v[64:67], v191 offset:16384
	ds_read_b128 v[68:71], v191 offset:16400
	ds_read_b128 v[72:75], v191 offset:18432
	ds_read_b128 v[76:79], v191 offset:18448
	ds_read_b128 v[84:87], v191
	ds_read_b128 v[88:91], v191 offset:16
	ds_read_b128 v[96:99], v191 offset:4096
	ds_read_b128 v[100:103], v191 offset:4112
	ds_read_b128 v[108:111], v191 offset:8192
	ds_read_b128 v[112:115], v191 offset:8208
	ds_read_b128 v[120:123], v191 offset:12288
	ds_read_b128 v[124:127], v191 offset:12304
	v_mul_u32_u24_e32 v24, 0x90, v209
	v_add_u32_e32 v24, v24, v211
	s_waitcnt vmcnt(0)
	ds_write_b128 v24, v[44:47] offset:18432
	ds_write_b128 v24, v[48:51] offset:27648
	v_cmp_gt_i32_e32 vcc, s66, v23
	s_and_saveexec_b64 s[2:3], vcc
	v_cmp_gt_u32_e32 vcc, 8, v23
	s_nop 1
	v_cndmask_b32_e32 v2, 0, v205, vcc
	v_mov_b32_e32 v3, v2
	v_mov_b32_e32 v4, v2
	v_mov_b32_e32 v5, v2
	ds_write_b128 v24, v[2:5] offset:36864
	s_or_b64 exec, exec, s[2:3]
	ds_write_b128 v24, v[52:55] offset:39168
	ds_write_b128 v24, v[56:59] offset:48384
	v_cmp_gt_u32_e32 vcc, 8, v23
	s_and_saveexec_b64 s[2:3], vcc
	ds_write_b128 v24, v[60:63] offset:57600
	s_or_b64 exec, exec, s[2:3]
	s_movk_i32 s4, 0x78
	v_cmp_gt_i32_e32 vcc, s4, v23
	s_and_saveexec_b64 s[2:3], vcc
	v_mov_b32_e32 v2, 0
	v_mov_b32_e32 v3, 0
	v_mov_b32_e32 v4, 0
	v_mov_b32_e32 v5, 0
	ds_write_b128 v24, v[2:5] offset:57744
	s_or_b64 exec, exec, s[2:3]
	s_waitcnt lgkmcnt(0)
	ds_read_b128 v[132:135], v191 offset:2048
	ds_read_b128 v[136:139], v191 offset:2064
	ds_read_b128 v[144:147], v191 offset:6144
	ds_read_b128 v[148:151], v191 offset:6160
	ds_read_b128 v[156:159], v191 offset:10240
	ds_read_b128 v[160:163], v191 offset:10256
	ds_read_b128 v[182:185], v191 offset:14336
	ds_read_b128 v[186:189], v191 offset:14352
	v_mov_b32_e32 v4, v64
	v_mov_b32_e32 v5, v65
	v_mov_b32_e32 v6, v66
	v_mov_b32_e32 v7, v67
	v_mov_b32_e32 v0, v68
	v_mov_b32_e32 v1, v69
	v_mov_b32_e32 v2, v70
	v_mov_b32_e32 v3, v71
	s_and_saveexec_b64 s[2:3], s[46:47]
	v_lshlrev_b32_e32 v12, 16, v80
	v_and_b32_e32 v13, 0xffff0000, v80
	v_pk_fma_f32 v[4:5], v[84:85], v[12:13], v[4:5]
	v_lshlrev_b32_e32 v14, 16, v81
	v_and_b32_e32 v15, 0xffff0000, v81
	v_pk_fma_f32 v[6:7], v[86:87], v[14:15], v[6:7]
	v_lshlrev_b32_e32 v12, 16, v82
	v_and_b32_e32 v13, 0xffff0000, v82
	v_pk_fma_f32 v[0:1], v[88:89], v[12:13], v[0:1]
	v_lshlrev_b32_e32 v14, 16, v83
	v_and_b32_e32 v15, 0xffff0000, v83
	v_pk_fma_f32 v[2:3], v[90:91], v[14:15], v[2:3]
	s_or_b64 exec, exec, s[2:3]
	s_and_saveexec_b64 s[2:3], s[48:49]
	v_lshlrev_b32_e32 v12, 16, v92
	v_and_b32_e32 v13, 0xffff0000, v92
	v_pk_fma_f32 v[4:5], v[96:97], v[12:13], v[4:5]
	v_lshlrev_b32_e32 v14, 16, v93
	v_and_b32_e32 v15, 0xffff0000, v93
	v_pk_fma_f32 v[6:7], v[98:99], v[14:15], v[6:7]
	v_lshlrev_b32_e32 v12, 16, v94
	v_and_b32_e32 v13, 0xffff0000, v94
	v_pk_fma_f32 v[0:1], v[100:101], v[12:13], v[0:1]
	v_lshlrev_b32_e32 v14, 16, v95
	v_and_b32_e32 v15, 0xffff0000, v95
	v_pk_fma_f32 v[2:3], v[102:103], v[14:15], v[2:3]
	s_or_b64 exec, exec, s[2:3]
	s_and_saveexec_b64 s[2:3], s[50:51]
	v_lshlrev_b32_e32 v12, 16, v104
	v_and_b32_e32 v13, 0xffff0000, v104
	v_pk_fma_f32 v[4:5], v[108:109], v[12:13], v[4:5]
	v_lshlrev_b32_e32 v14, 16, v105
	v_and_b32_e32 v15, 0xffff0000, v105
	v_pk_fma_f32 v[6:7], v[110:111], v[14:15], v[6:7]
	v_lshlrev_b32_e32 v12, 16, v106
	v_and_b32_e32 v13, 0xffff0000, v106
	v_pk_fma_f32 v[0:1], v[112:113], v[12:13], v[0:1]
	v_lshlrev_b32_e32 v14, 16, v107
	v_and_b32_e32 v15, 0xffff0000, v107
	v_pk_fma_f32 v[2:3], v[114:115], v[14:15], v[2:3]
	s_or_b64 exec, exec, s[2:3]
	v_lshlrev_b32_e32 v12, 16, v116
	v_and_b32_e32 v13, 0xffff0000, v116
	v_pk_fma_f32 v[4:5], v[120:121], v[12:13], v[4:5]
	v_lshlrev_b32_e32 v14, 16, v117
	v_and_b32_e32 v15, 0xffff0000, v117
	v_pk_fma_f32 v[6:7], v[122:123], v[14:15], v[6:7]
	v_lshlrev_b32_e32 v12, 16, v118
	v_and_b32_e32 v13, 0xffff0000, v118
	v_pk_fma_f32 v[0:1], v[124:125], v[12:13], v[0:1]
	v_lshlrev_b32_e32 v14, 16, v119
	v_and_b32_e32 v15, 0xffff0000, v119
	v_pk_fma_f32 v[2:3], v[126:127], v[14:15], v[2:3]
	v_mul_f32_e32 v20, 0xbfb8aa3b, v4
	v_mul_f32_e32 v21, 0xbfb8aa3b, v5
	v_mul_f32_e32 v26, 0xbfb8aa3b, v6
	v_mul_f32_e32 v27, 0xbfb8aa3b, v7
	v_mul_f32_e32 v28, 0xbfb8aa3b, v0
	v_mul_f32_e32 v29, 0xbfb8aa3b, v1
	v_exp_f32_e32 v20, v20
	v_exp_f32_e32 v21, v21
	v_exp_f32_e32 v26, v26
	v_exp_f32_e32 v27, v27
	v_exp_f32_e32 v28, v28
	v_exp_f32_e32 v29, v29
	v_mul_f32_e32 v30, 0xbfb8aa3b, v2
	v_mul_f32_e32 v31, 0xbfb8aa3b, v3
	v_exp_f32_e32 v30, v30
	v_exp_f32_e32 v31, v31
	v_add_f32_e32 v20, 1.0, v20
	v_add_f32_e32 v21, 1.0, v21
	v_add_f32_e32 v26, 1.0, v26
	v_add_f32_e32 v27, 1.0, v27
	v_add_f32_e32 v28, 1.0, v28
	v_add_f32_e32 v29, 1.0, v29
	v_rcp_f32_e32 v20, v20
	v_rcp_f32_e32 v21, v21
	v_rcp_f32_e32 v26, v26
	v_rcp_f32_e32 v27, v27
	v_rcp_f32_e32 v28, v28
	v_rcp_f32_e32 v29, v29
	v_add_f32_e32 v30, 1.0, v30
	v_add_f32_e32 v31, 1.0, v31
	v_rcp_f32_e32 v30, v30
	v_rcp_f32_e32 v31, v31
	v_pk_mul_f32 v[4:5], v[4:5], v[20:21]
	s_mov_b32 s10, 0x3e000000
	v_pk_mul_f32 v[6:7], v[6:7], v[26:27]
	v_pk_mul_f32 v[0:1], v[0:1], v[28:29]
	v_pk_mul_f32 v[4:5], v[4:5], s[10:11] op_sel_hi:[1,0]
	v_pk_mul_f32 v[6:7], v[6:7], s[10:11] op_sel_hi:[1,0]
	v_pk_mul_f32 v[0:1], v[0:1], s[10:11] op_sel_hi:[1,0]
	v_cvt_pk_bf16_f32 v4, v4, v5
	v_cvt_pk_bf16_f32 v5, v6, v7
	v_cvt_pk_bf16_f32 v6, v0, v1
	v_pk_mul_f32 v[0:1], v[2:3], v[30:31]
	v_pk_mul_f32 v[0:1], v[0:1], s[10:11] op_sel_hi:[1,0]
	v_cvt_pk_bf16_f32 v7, v0, v1
	ds_write_b128 v24, v[4:7]
	s_waitcnt lgkmcnt(0)
	v_mov_b32_e32 v4, v72
	v_mov_b32_e32 v5, v73
	v_mov_b32_e32 v6, v74
	v_mov_b32_e32 v7, v75
	v_mov_b32_e32 v0, v76
	v_mov_b32_e32 v1, v77
	v_mov_b32_e32 v2, v78
	v_mov_b32_e32 v3, v79
	s_and_saveexec_b64 s[2:3], s[46:47]
	v_lshlrev_b32_e32 v12, 16, v128
	v_and_b32_e32 v13, 0xffff0000, v128
	v_pk_fma_f32 v[4:5], v[132:133], v[12:13], v[4:5]
	v_lshlrev_b32_e32 v14, 16, v129
	v_and_b32_e32 v15, 0xffff0000, v129
	v_pk_fma_f32 v[6:7], v[134:135], v[14:15], v[6:7]
	v_lshlrev_b32_e32 v12, 16, v130
	v_and_b32_e32 v13, 0xffff0000, v130
	v_pk_fma_f32 v[0:1], v[136:137], v[12:13], v[0:1]
	v_lshlrev_b32_e32 v14, 16, v131
	v_and_b32_e32 v15, 0xffff0000, v131
	v_pk_fma_f32 v[2:3], v[138:139], v[14:15], v[2:3]
	s_or_b64 exec, exec, s[2:3]
	s_and_saveexec_b64 s[2:3], s[48:49]
	v_lshlrev_b32_e32 v12, 16, v140
	v_and_b32_e32 v13, 0xffff0000, v140
	v_pk_fma_f32 v[4:5], v[144:145], v[12:13], v[4:5]
	v_lshlrev_b32_e32 v14, 16, v141
	v_and_b32_e32 v15, 0xffff0000, v141
	v_pk_fma_f32 v[6:7], v[146:147], v[14:15], v[6:7]
	v_lshlrev_b32_e32 v12, 16, v142
	v_and_b32_e32 v13, 0xffff0000, v142
	v_pk_fma_f32 v[0:1], v[148:149], v[12:13], v[0:1]
	v_lshlrev_b32_e32 v14, 16, v143
	v_and_b32_e32 v15, 0xffff0000, v143
	v_pk_fma_f32 v[2:3], v[150:151], v[14:15], v[2:3]
	s_or_b64 exec, exec, s[2:3]
	s_and_saveexec_b64 s[2:3], s[50:51]
	v_lshlrev_b32_e32 v12, 16, v152
	v_and_b32_e32 v13, 0xffff0000, v152
	v_pk_fma_f32 v[4:5], v[156:157], v[12:13], v[4:5]
	v_lshlrev_b32_e32 v14, 16, v153
	v_and_b32_e32 v15, 0xffff0000, v153
	v_pk_fma_f32 v[6:7], v[158:159], v[14:15], v[6:7]
	v_lshlrev_b32_e32 v12, 16, v154
	v_and_b32_e32 v13, 0xffff0000, v154
	v_pk_fma_f32 v[0:1], v[160:161], v[12:13], v[0:1]
	v_lshlrev_b32_e32 v14, 16, v155
	v_and_b32_e32 v15, 0xffff0000, v155
	v_pk_fma_f32 v[2:3], v[162:163], v[14:15], v[2:3]
	s_or_b64 exec, exec, s[2:3]
	v_lshlrev_b32_e32 v12, 16, v178
	v_and_b32_e32 v13, 0xffff0000, v178
	v_pk_fma_f32 v[4:5], v[182:183], v[12:13], v[4:5]
	v_lshlrev_b32_e32 v14, 16, v179
	v_and_b32_e32 v15, 0xffff0000, v179
	v_pk_fma_f32 v[6:7], v[184:185], v[14:15], v[6:7]
	v_lshlrev_b32_e32 v12, 16, v180
	v_and_b32_e32 v13, 0xffff0000, v180
	v_pk_fma_f32 v[0:1], v[186:187], v[12:13], v[0:1]
	v_lshlrev_b32_e32 v14, 16, v181
	v_and_b32_e32 v15, 0xffff0000, v181
	v_pk_fma_f32 v[2:3], v[188:189], v[14:15], v[2:3]
	s_waitcnt vmcnt(0)
	v_mul_f32_e32 v8, 0xbfb8aa3b, v4
	v_exp_f32_e32 v8, v8
	s_bfe_u32 s5, s40, 0x20006
	v_and_b32_e32 v9, 15, v23
	s_ashr_i32 s6, s40, 7
	v_add_f32_e32 v8, 1.0, v8
	v_rcp_f32_e32 v10, v8
	v_mul_f32_e32 v8, 0xbfb8aa3b, v5
	v_exp_f32_e32 v8, v8
	s_lshl_b32 s4, s5, 4
	s_and_b32 s2, s6, -2
	s_cmp_gt_i32 s2, s5
	v_add_f32_e32 v8, 1.0, v8
	v_rcp_f32_e32 v11, v8
	v_mul_f32_e32 v8, 0xbfb8aa3b, v6
	v_exp_f32_e32 v8, v8
	v_pk_mul_f32 v[4:5], v[4:5], v[10:11]
	v_add_f32_e32 v8, 1.0, v8
	v_rcp_f32_e32 v10, v8
	v_mul_f32_e32 v8, 0xbfb8aa3b, v7
	v_exp_f32_e32 v8, v8
	s_nop 0
	v_add_f32_e32 v8, 1.0, v8
	v_rcp_f32_e32 v11, v8
	v_mul_f32_e32 v8, 0xbfb8aa3b, v0
	v_exp_f32_e32 v8, v8
	v_pk_mul_f32 v[6:7], v[6:7], v[10:11]
	v_add_f32_e32 v8, 1.0, v8
	v_rcp_f32_e32 v10, v8
	v_mul_f32_e32 v8, 0xbfb8aa3b, v1
	v_exp_f32_e32 v8, v8
	s_nop 0
	v_add_f32_e32 v8, 1.0, v8
	v_rcp_f32_e32 v11, v8
	s_nop 0
	v_pk_mul_f32 v[10:11], v[0:1], v[10:11]
	v_mul_f32_e32 v0, 0xbfb8aa3b, v2
	v_mul_f32_e32 v1, 0xbfb8aa3b, v3
	v_exp_f32_e32 v0, v0
	v_exp_f32_e32 v1, v1
	v_add_f32_e32 v0, 1.0, v0
	v_add_f32_e32 v1, 1.0, v1
	v_rcp_f32_e32 v0, v0
	v_rcp_f32_e32 v1, v1
	s_nop 0
	v_pk_mul_f32 v[12:13], v[2:3], v[0:1]
	v_cvt_pk_bf16_f32 v0, v4, v5
	v_cvt_pk_bf16_f32 v1, v6, v7
	v_cvt_pk_bf16_f32 v2, v10, v11
	v_cvt_pk_bf16_f32 v3, v12, v13
	ds_write_b128 v24, v[0:3] offset:9216
	v_and_b32_e32 v1, 48, v22
	v_or_b32_e32 v0, s4, v9
	v_add_u32_e32 v8, 0, v1
	v_mad_u32_u24 v10, v0, s84, v8
	v_lshl_or_b32 v12, s2, 4, v9
	v_mov_b32_e32 v5, 0
	v_mov_b32_e32 v0, 0
	v_mov_b32_e32 v1, 0
	v_mov_b32_e32 v2, 0
	v_mov_b32_e32 v3, 0
	s_waitcnt lgkmcnt(0)
	s_barrier
	s_cbranch_scc1 .LBB0_474
	v_mad_u64_u32 v[6:7], s[2:3], v12, s84, v[8:9]
	ds_read_b128 v[0:3], v10
	ds_read_b128 v[14:17], v6 offset:9216
	s_waitcnt lgkmcnt(0)
	v_mfma_f32_16x16x32_bf16 v[0:3], v[0:3], v[14:17], 0
	ds_read_b128 v[14:17], v10 offset:64
	ds_read_b128 v[18:21], v6 offset:9280
	s_waitcnt lgkmcnt(0)
	v_mfma_f32_16x16x32_bf16 v[0:3], v[14:17], v[18:21], v[0:3]
